# select: per-item completion flag and its store drain posted one item late (overlaps the mask write-through with the next item's first loads)
# speedup vs baseline: 1.0648x; 1.0033x over previous
.LBB0_112:
	s_mov_b32 s100, -1
	s_abs_i32 s4, s97
	v_cvt_f32_u32_e32 v0, s4
	s_add_i32 s5, s97, 0x3ff
	s_sub_i32 s6, 0xfffffc01, s97
	s_xor_b32 s7, s5, s97
	v_rcp_iflag_f32_e32 v0, v0
	s_max_i32 s5, s5, s6
	s_sub_i32 s6, 0, s4
	s_ashr_i32 s7, s7, 31
	v_mul_f32_e32 v0, 0x4f7ffffe, v0
	v_cvt_u32_f32_e32 v0, v0
	v_and_b32_e32 v135, 15, v166
	v_readlane_b32 s38, v255, 11
	v_readlane_b32 s39, v255, 12
	v_readfirstlane_b32 s8, v0
	s_mul_i32 s6, s6, s8
	s_mul_hi_u32 s6, s8, s6
	s_add_i32 s8, s8, s6
	s_mul_hi_u32 s6, s5, s8
	s_mul_i32 s8, s6, s4
	s_sub_i32 s5, s5, s8
	s_add_i32 s9, s6, 1
	s_sub_i32 s8, s5, s4
	s_cmp_ge_u32 s5, s4
	s_cselect_b32 s6, s9, s6
	s_cselect_b32 s5, s8, s5
	s_add_i32 s8, s6, 1
	s_cmp_ge_u32 s5, s4
	s_cselect_b32 s4, s8, s6
	s_xor_b32 s4, s4, s7
	s_sub_i32 s77, s4, s7
	s_cmp_lt_i32 s77, 1
	s_cbranch_scc1 .LBB0_243
	v_readlane_b32 s4, v255, 28
	v_readlane_b32 s5, v255, 29
	s_lshl_b32 s4, s4, 10
	s_ashr_i32 s5, s4, 31
	s_lshl_b64 s[4:5], s[4:5], 2
	s_add_u32 s4, s78, s4
	s_addc_u32 s5, s79, s5
	s_add_u32 s80, s4, 0xfa08000
	s_addc_u32 s84, s5, 0
	s_not_b32 s4, s76
	s_add_i32 s86, s77, -1
	s_add_i32 s87, s97, s4
	s_bitcmp0_b32 s86, 0
	s_cselect_b32 s4, s76, s87
	s_mul_i32 s5, s86, s97
	s_add_i32 s4, s4, s5
	s_min_i32 s4, s4, 0x3ff
	s_lshl_b32 s5, s4, 12
	s_lshl_b32 s4, s4, 2
	s_and_b32 s4, s4, -16
	s_and_b32 s5, s5, 0x3000
	s_ashr_i32 s6, s4, 31
	v_ashrrev_i32_e32 v0, 1, v166
	s_add_u32 s4, s5, s4
	s_waitcnt vmcnt(2)
	v_and_b32_e32 v66, -8, v0
	v_or_b32_e32 v0, s4, v135
	v_mov_b64_e32 v[2:3], s[0:1]
	s_addc_u32 s6, 0, s6
	v_mad_u64_u32 v[34:35], s[4:5], v0, s33, v[2:3]
	v_ashrrev_i32_e32 v67, 31, v66
	v_mad_i32_i24 v35, s6, v218, v35
	v_lshl_add_u64 v[26:27], v[66:67], 1, v[34:35]
	s_mov_b64 s[4:5], 0x1000
	v_lshl_add_u64 v[28:29], v[26:27], 0, s[4:5]
	s_movk_i32 s4, 0x1000
	global_load_dwordx4 v[2:5], v[28:29], off offset:384
	global_load_dwordx4 v[6:9], v[28:29], off offset:320
	global_load_dwordx4 v[10:13], v[28:29], off offset:256
	global_load_dwordx4 v[14:17], v[28:29], off offset:192
	global_load_dwordx4 v[18:21], v[28:29], off offset:128
	global_load_dwordx4 v[22:25], v[28:29], off offset:64
	s_waitcnt vmcnt(6)
	v_add_co_u32_e32 v30, vcc, s4, v26
	v_and_b32_e32 v0, 64, v179
	s_nop 0
	v_addc_co_u32_e32 v31, vcc, 0, v27, vcc
	v_add_co_u32_e32 v34, vcc, s4, v34
	global_load_dwordx4 v[26:29], v[28:29], off offset:448
	s_nop 0
	global_load_dwordx4 v[30:33], v[30:31], off
	v_addc_co_u32_e32 v35, vcc, 0, v35, vcc
	global_load_dwordx2 v[70:71], v[34:35], off offset:1664
	v_add_u32_e32 v34, -1, v179
	v_cmp_lt_i32_e32 vcc, v34, v0
	s_mov_b32 s88, 0
	s_nop 0
	v_cndmask_b32_e32 v34, v34, v179, vcc
	v_lshlrev_b32_e32 v100, 2, v34
	v_add_u32_e32 v34, -2, v179
	v_cmp_lt_i32_e32 vcc, v34, v0
	s_nop 1
	v_cndmask_b32_e32 v34, v34, v179, vcc
	v_lshlrev_b32_e32 v101, 2, v34
	v_add_u32_e32 v34, -4, v179
	v_cmp_lt_i32_e32 vcc, v34, v0
	s_nop 1
	v_cndmask_b32_e32 v34, v34, v179, vcc
	v_lshlrev_b32_e32 v102, 2, v34
	v_add_u32_e32 v34, -8, v179
	v_cmp_lt_i32_e32 vcc, v34, v0
	s_nop 1
	v_cndmask_b32_e32 v34, v34, v179, vcc
	v_lshlrev_b32_e32 v103, 2, v34
	v_add_u32_e32 v34, -16, v179
	v_cmp_lt_i32_e32 vcc, v34, v0
	s_nop 1
	v_cndmask_b32_e32 v34, v34, v179, vcc
	v_lshlrev_b32_e32 v104, 2, v34
	v_subrev_u32_e32 v34, 32, v179
	v_cmp_lt_i32_e32 vcc, v34, v0
	s_nop 1
	v_cndmask_b32_e32 v0, v34, v179, vcc
	v_lshlrev_b32_e32 v105, 2, v0
	s_branch .LBB0_116

.LBB0_116:
	s_sub_i32 s4, s86, s88
	s_bitcmp0_b32 s4, 0
	s_mul_i32 s5, s4, s97
	s_cselect_b32 s6, s76, s87
	s_add_i32 s74, s6, s5
	s_cmpk_gt_i32 s74, 0x3ff
	s_cbranch_scc1 .LBB0_115
	s_max_i32 s4, s4, 1
	s_add_i32 s4, s4, -1
	s_bitcmp0_b32 s4, 0
	s_cselect_b32 s5, s76, s87
	s_mul_i32 s4, s4, s97
	s_add_i32 s7, s5, s4
	s_lshl_b32 s4, s74, 2
	s_ashr_i32 s8, s74, 2
	s_and_b32 s20, s74, 3
	s_and_b32 s9, s4, -16
	s_add_i32 s4, s8, 0x80
	v_mov_b32_e32 v68, v166
	v_readlane_b32 s6, v255, 21
	s_ashr_i32 s10, s4, 7
	s_lshl_b32 s4, s20, 19
	v_readlane_b32 s12, v255, 36
	v_readlane_b32 s13, v255, 37
	v_and_b32_e32 v38, 15, v68
	s_add_u32 s4, s12, s4
	s_addc_u32 s5, s13, 0
	v_lshlrev_b32_e32 v0, 6, v38
	v_lshl_add_u64 v[34:35], s[4:5], 0, v[0:1]
	s_movk_i32 s4, 0x2420
	v_mad_u32_u24 v69, v38, s4, 0
	s_min_i32 s4, s7, 0x3ff
	s_lshl_b32 s5, s4, 12
	s_lshl_b32 s4, s4, 2
	v_ashrrev_i32_e32 v0, 1, v68
	s_lshl_b32 s75, s6, 1
	s_and_b32 s4, s4, -16
	v_and_b32_e32 v36, -8, v0
	s_add_i32 s75, s75, s9
	s_and_b32 s5, s5, 0x3000
	s_ashr_i32 s7, s4, 31
	v_ashrrev_i32_e32 v37, 31, v36
	s_add_u32 s4, s5, s4
	s_waitcnt vmcnt(11)
	v_lshl_add_u64 v[80:81], v[36:37], 1, v[34:35]
	v_or_b32_e32 v0, s4, v135
	v_mov_b64_e32 v[34:35], s[0:1]
	s_addc_u32 s7, 0, s7
	v_mad_u64_u32 v[34:35], s[4:5], v0, s33, v[34:35]
	v_mad_i32_i24 v35, s7, v218, v35
	v_lshl_add_u64 v[36:37], v[66:67], 1, v[34:35]
	s_mov_b64 s[4:5], 0x1000
	v_lshl_add_u64 v[82:83], v[36:37], 0, s[4:5]
	s_mov_b64 s[4:5], 0x1680
	v_lshl_add_u64 v[84:85], v[34:35], 0, s[4:5]
	s_mul_i32 s4, s6, 0x4840
	s_add_i32 s9, s4, 0
	s_movk_i32 s4, 0x90
	v_mov_b32_e32 v86, s6
	s_cmp_lt_i32 s100, 0
	s_cbranch_scc0 .Lsf_pend
	s_waitcnt vmcnt(0)
	s_branch .Lsf_cont

.Lsf_cont:
	v_lshlrev_b32_e32 v72, 16, v70
	v_and_b32_e32 v74, 0xffff0000, v70
	v_lshlrev_b32_e32 v76, 16, v71
	v_and_b32_e32 v78, 0xffff0000, v71
	v_mov_b32_e32 v106, s75
	v_and_b32_e32 v171, -16, v68
	v_mul_lo_u32 v0, v68, s4
	s_cmp_lt_i32 s10, 1
	v_lshlrev_b32_e32 v172, 5, v68
	s_cbranch_scc1 .LBB0_128
	s_min_i32 s11, s8, 0x7f
	v_cmp_ge_i32_e32 vcc, s11, v86
	s_and_saveexec_b64 s[4:5], vcc
	s_cbranch_execz .LBB0_121
	v_add_u32_e64 v34, s6, 8
	v_min_i32_e32 v34, s11, v34
	v_ashrrev_i32_e32 v35, 31, v34
	v_ashrrev_i32_e64 v87, 31, s6
	v_lshlrev_b64 v[34:35], 11, v[34:35]
	v_lshlrev_b64 v[42:43], 11, v[86:87]
	v_lshl_add_u64 v[38:39], v[80:81], 0, v[34:35]
	v_lshl_add_u64 v[46:47], v[80:81], 0, v[42:43]
	global_load_dwordx4 v[34:37], v[38:39], off offset:1024
	s_nop 0
	global_load_dwordx4 v[38:41], v[38:39], off
	s_nop 0
	global_load_dwordx4 v[42:45], v[46:47], off offset:1024
	s_nop 0
	global_load_dwordx4 v[46:49], v[46:47], off
	v_mov_b32_e32 v79, v78
	v_mov_b32_e32 v88, v78
	v_mov_b32_e32 v89, v78
	v_mov_b32_e32 v77, v76
	v_mov_b32_e32 v90, v76
	v_mov_b32_e32 v91, v76
	v_mov_b32_e32 v75, v74
	v_mov_b32_e32 v92, v74
	v_mov_b32_e32 v93, v74
	v_mov_b32_e32 v73, v72
	v_mov_b32_e32 v94, v72
	v_mov_b32_e32 v95, v72
	s_mov_b64 s[6:7], 0
	v_mov_b32_e32 v87, v86

.LBB0_121:
	s_or_b64 exec, exec, s[4:5]
	s_waitcnt vmcnt(0) lgkmcnt(0)
	s_cmp_lt_i32 s100, 0
	s_cbranch_scc1 .Lsf_none
	s_lshl_b32 s4, s100, 2
	s_add_u32 s4, s80, s4
	s_addc_u32 s5, s84, 0
	v_mov_b32_e32 v34, 1
	s_mov_b64 vcc, exec
	s_mov_b64 exec, 1
	global_atomic_add v1, v34, s[4:5]
	s_mov_b64 exec, vcc
	s_mov_b32 s100, -1
.Lsf_none:
	s_cmp_lg_u32 s10, 1
	s_barrier
	s_cbranch_scc1 .LBB0_123
	global_load_dwordx4 v[30:33], v[82:83], off
	global_load_dwordx4 v[22:25], v[82:83], off offset:64
	global_load_dwordx4 v[18:21], v[82:83], off offset:128
	global_load_dwordx4 v[14:17], v[82:83], off offset:192
	global_load_dwordx4 v[10:13], v[82:83], off offset:256
	global_load_dwordx4 v[6:9], v[82:83], off offset:320
	global_load_dwordx4 v[2:5], v[82:83], off offset:384
	global_load_dwordx4 v[26:29], v[82:83], off offset:448
	global_load_dwordx2 v[70:71], v[84:85], off

.LBB0_238:
	s_or_b64 exec, exec, s[70:71]
	s_mov_b32 s100, s74
	s_branch .LBB0_115
.LBB0_243:
	s_waitcnt vmcnt(0)
	s_cmp_lt_i32 s100, 0
	s_cbranch_scc1 .Lsf_end
	s_lshl_b32 s4, s100, 2
	s_add_u32 s4, s80, s4
	s_addc_u32 s5, s84, 0
	v_mov_b32_e32 v34, 1
	s_mov_b64 vcc, exec
	s_mov_b64 exec, 1
	global_atomic_add v1, v34, s[4:5]
	s_mov_b64 exec, vcc
	s_mov_b32 s100, -1
.Lsf_end:
	v_lshl_add_u32 v2, s76, 9, v247
	s_mov_b32 s4, 0x80000
	v_cmp_gt_i32_e32 vcc, s4, v2
	s_barrier
	s_and_saveexec_b64 s[4:5], vcc
	v_readlane_b32 s14, v255, 30
	v_readlane_b32 s15, v255, 31
	s_cbranch_execz .LBB0_246
	v_readlane_b32 s6, v255, 22
	v_readlane_b32 s7, v255, 23
	s_load_dwordx2 s[6:7], s[6:7], 0x18
	v_readlane_b32 s8, v255, 28
	v_readlane_b32 s9, v255, 29
	s_mulk_i32 s8, 0x300
	s_ashr_i32 s9, s8, 31
	s_lshl_b64 s[8:9], s[8:9], 2
	s_waitcnt lgkmcnt(0)
	s_add_u32 s6, s6, s8
	s_addc_u32 s7, s7, s9
	s_lshl_b32 s10, s97, 9
	v_lshlrev_b32_e32 v3, 3, v2
	s_lshl_b32 s11, s97, 12
	s_mov_b64 s[8:9], 0
